# v14 + attention row max as a 16-instruction v_max3 chain
# speedup vs baseline: 1.0104x; 1.0037x over previous
.LBB0_1433:
	s_and_b64 vcc, exec, s[28:29]
	s_cbranch_vccz .LBB0_1406
	s_barrier
	s_branch .LBB0_1406
	s_nop 0
	s_nop 0
	s_nop 0
